# DSA select: first histogram pass processes 8 key blocks per trip (8 LDS reads in flight, one wait, 8 masked ds_add)
# speedup vs baseline: 1.0097x; 1.0051x over previous
.Lsel8_top:
	s_cmp_lt_u32 s35, 8
	s_cbranch_scc1 .LBB0_202
	ds_read_u8 v208, v2 offset:1
	ds_read_u8 v209, v2 offset:129
	ds_read_u8 v210, v2 offset:257
	ds_read_u8 v211, v2 offset:385
	ds_read_u8 v212, v2 offset:513
	ds_read_u8 v213, v2 offset:641
	ds_read_u8 v214, v2 offset:769
	ds_read_u8 v215, v2 offset:897
	s_waitcnt lgkmcnt(0)
	v_cmp_ge_u32_e32 vcc, s50, v3
	s_and_saveexec_b64 s[28:29], vcc
	v_lshl_add_u32 v208, v208, 2, s38
	ds_add_u32 v208, v196
	s_or_b64 exec, exec, s[28:29]
	v_add_u32_e32 v216, 64, v3
	v_cmp_ge_u32_e32 vcc, s50, v216
	s_and_saveexec_b64 s[28:29], vcc
	v_lshl_add_u32 v209, v209, 2, s38
	ds_add_u32 v209, v196
	s_or_b64 exec, exec, s[28:29]
	v_add_u32_e32 v216, 128, v3
	v_cmp_ge_u32_e32 vcc, s50, v216
	s_and_saveexec_b64 s[28:29], vcc
	v_lshl_add_u32 v210, v210, 2, s38
	ds_add_u32 v210, v196
	s_or_b64 exec, exec, s[28:29]
	v_add_u32_e32 v216, 192, v3
	v_cmp_ge_u32_e32 vcc, s50, v216
	s_and_saveexec_b64 s[28:29], vcc
	v_lshl_add_u32 v211, v211, 2, s38
	ds_add_u32 v211, v196
	s_or_b64 exec, exec, s[28:29]
	v_add_u32_e32 v216, 256, v3
	v_cmp_ge_u32_e32 vcc, s50, v216
	s_and_saveexec_b64 s[28:29], vcc
	v_lshl_add_u32 v212, v212, 2, s38
	ds_add_u32 v212, v196
	s_or_b64 exec, exec, s[28:29]
	v_add_u32_e32 v216, 320, v3
	v_cmp_ge_u32_e32 vcc, s50, v216
	s_and_saveexec_b64 s[28:29], vcc
	v_lshl_add_u32 v213, v213, 2, s38
	ds_add_u32 v213, v196
	s_or_b64 exec, exec, s[28:29]
	v_add_u32_e32 v216, 384, v3
	v_cmp_ge_u32_e32 vcc, s50, v216
	s_and_saveexec_b64 s[28:29], vcc
	v_lshl_add_u32 v214, v214, 2, s38
	ds_add_u32 v214, v196
	s_or_b64 exec, exec, s[28:29]
	v_add_u32_e32 v216, 448, v3
	v_cmp_ge_u32_e32 vcc, s50, v216
	s_and_saveexec_b64 s[28:29], vcc
	v_lshl_add_u32 v215, v215, 2, s38
	ds_add_u32 v215, v196
	s_or_b64 exec, exec, s[28:29]
	s_add_i32 s35, s35, -8
	v_add_u32_e32 v2, 0x400, v2
	v_add_u32_e32 v3, 0x200, v3
	s_cmp_eq_u32 s35, 0
	s_cbranch_scc1 .LBB0_206
	s_branch .Lsel8_top
